# selw: per-lane selection words preloaded into VGPRs once per unit; sel loop head tests block bits without LDS round trips; K frag reads issued first
# baseline (speedup 1.0000x reference)
.Lradix_done:
	v_cmp_eq_u32_e64 s[26:27], s31, v3
	v_cmp_eq_u32_e64 s[24:25], s31, v2
	s_and_b64 s[78:79], s[20:21], s[26:27]
	v_cmp_lt_u32_e64 s[0:1], s31, v3
	v_cmp_lt_u32_e64 s[22:23], s31, v2
	v_cndmask_b32_e64 v2, 0, 1, s[78:79]
	s_and_b64 s[80:81], vcc, s[24:25]
	v_cmp_ne_u32_e64 s[26:27], 0, v2
	v_cndmask_b32_e64 v2, 0, 1, s[80:81]
	s_and_b64 s[82:83], s[20:21], s[0:1]
	v_cmp_ne_u32_e64 s[24:25], 0, v2
	v_cndmask_b32_e64 v2, 0, 1, s[82:83]
	s_and_b64 s[22:23], vcc, s[22:23]
	v_cmp_ne_u32_e64 s[0:1], 0, v2
	v_cndmask_b32_e64 v2, 0, 1, s[22:23]
	s_bcnt1_i32_b64 s31, s[0:1]
	v_cmp_ne_u32_e64 s[0:1], 0, v2
	v_and_b32_e32 v3, s26, v126
	s_bcnt1_i32_b64 s0, s[0:1]
	v_and_b32_e32 v2, s27, v125
	v_bcnt_u32_b32 v3, v3, 0
	v_and_b32_e32 v7, s24, v126
	s_add_i32 s31, s31, s0
	v_bcnt_u32_b32 v2, v2, v3
	v_and_b32_e32 v3, s25, v125
	v_bcnt_u32_b32 v7, v7, 0
	s_sub_i32 s31, 16, s31
	s_bcnt1_i32_b64 s0, s[26:27]
	v_bcnt_u32_b32 v3, v3, v7
	v_add_u32_e32 v3, s0, v3
	v_cmp_gt_i32_e64 s[0:1], s31, v2
	s_and_b64 s[0:1], s[78:79], s[0:1]
	s_or_b64 s[0:1], s[82:83], s[0:1]
	v_cndmask_b32_e64 v2, 0, 1, s[0:1]
	v_cmp_gt_i32_e64 s[0:1], s31, v3
	s_and_b64 s[0:1], s[80:81], s[0:1]
	s_or_b64 s[0:1], s[22:23], s[0:1]
	v_cmp_ne_u32_e64 s[24:25], 0, v2
	v_cndmask_b32_e64 v2, 0, 1, s[0:1]
	v_cmp_ne_u32_e64 s[0:1], 0, v2
	s_and_saveexec_b64 s[22:23], s[6:7]
	v_mov_b32_e32 v8, s24
	v_mov_b32_e32 v9, s25
	v_mov_b32_e32 v10, s0
	v_mov_b32_e32 v11, s1
	ds_write_b128 v175, v[8:11]
	s_or_b64 exec, exec, s[22:23]
	v_cmp_eq_u32_e64 s[26:27], s30, v1
	v_cmp_lt_u32_e64 s[0:1], s30, v1
	v_cmp_lt_u32_e64 s[22:23], s30, v0
	v_cmp_eq_u32_e64 s[24:25], s30, v0
	s_and_b64 s[30:31], s[20:21], s[26:27]
	v_cndmask_b32_e64 v0, 0, 1, s[30:31]
	s_and_b64 s[78:79], vcc, s[24:25]
	v_cmp_ne_u32_e64 s[26:27], 0, v0
	v_cndmask_b32_e64 v0, 0, 1, s[78:79]
	s_and_b64 s[20:21], s[20:21], s[0:1]
	v_cmp_ne_u32_e64 s[24:25], 0, v0
	v_cndmask_b32_e64 v0, 0, 1, s[20:21]
	v_cmp_ne_u32_e64 s[0:1], 0, v0
	s_bcnt1_i32_b64 s77, s[0:1]
	s_and_b64 s[0:1], vcc, s[22:23]
	v_cndmask_b32_e64 v0, 0, 1, s[0:1]
	v_cmp_ne_u32_e32 vcc, 0, v0
	v_and_b32_e32 v1, s26, v126
	s_bcnt1_i32_b64 s22, vcc
	v_and_b32_e32 v0, s27, v125
	v_bcnt_u32_b32 v1, v1, 0
	v_and_b32_e32 v2, s24, v126
	s_add_i32 s77, s77, s22
	v_bcnt_u32_b32 v0, v0, v1
	v_and_b32_e32 v1, s25, v125
	v_bcnt_u32_b32 v2, v2, 0
	s_sub_i32 s77, 16, s77
	s_bcnt1_i32_b64 s22, s[26:27]
	v_bcnt_u32_b32 v1, v1, v2
	v_add_u32_e32 v1, s22, v1
	v_cmp_gt_i32_e32 vcc, s77, v0
	s_and_b64 s[22:23], s[30:31], vcc
	v_cmp_gt_i32_e32 vcc, s77, v1
	s_or_b64 s[20:21], s[20:21], s[22:23]
	s_and_b64 s[22:23], s[78:79], vcc
	v_cndmask_b32_e64 v0, 0, 1, s[20:21]
	s_or_b64 s[0:1], s[0:1], s[22:23]
	v_cmp_ne_u32_e64 s[20:21], 0, v0
	v_cndmask_b32_e64 v0, 0, 1, s[0:1]
	v_cmp_ne_u32_e32 vcc, 0, v0
	s_and_saveexec_b64 s[0:1], s[6:7]
	v_mov_b32_e32 v0, s20
	v_mov_b32_e32 v1, s21
	v_mov_b32_e32 v2, vcc_lo
	v_mov_b32_e32 v3, vcc_hi
	ds_write_b128 v176, v[0:3]
	s_or_b64 exec, exec, s[0:1]
	s_waitcnt lgkmcnt(0)
	s_barrier
	ds_read_b32 v0, v157
	ds_read_b64 v[234:235], v160
	ds_read_b64 v[238:239], v160 offset:8
	v_xor_b32_e32 v1, 4, v180
	v_cmp_lt_i32_e32 vcc, v1, v6
	v_xor_b32_e32 v2, 8, v180
	s_nop 0
	v_cndmask_b32_e32 v1, v180, v1, vcc
	v_lshlrev_b32_e32 v1, 2, v1
	s_waitcnt lgkmcnt(0)
	ds_bpermute_b32 v1, v1, v0
	v_cmp_lt_i32_e32 vcc, v2, v6
	s_waitcnt lgkmcnt(0)
	v_or_b32_e32 v3, v0, v1
	v_cndmask_b32_e32 v2, v180, v2, vcc
	v_lshlrev_b32_e32 v2, 2, v2
	v_and_b32_e32 v7, v0, v1
	ds_bpermute_b32 v6, v2, v3
	ds_bpermute_b32 v2, v2, v7
	s_waitcnt lgkmcnt(1)
	v_or_b32_e32 v3, v3, v6
	s_waitcnt lgkmcnt(0)
	v_bitop3_b32 v0, v2, v0, v1 bitop3:0x80
	ds_bpermute_b32 v6, v4, v3
	ds_bpermute_b32 v1, v4, v0
	s_waitcnt lgkmcnt(1)
	v_or_b32_e32 v3, v3, v6
	s_waitcnt lgkmcnt(0)
	v_bitop3_b32 v2, v2, v1, v7 bitop3:0x80
	ds_bpermute_b32 v4, v5, v3
	ds_bpermute_b32 v2, v5, v2
	s_waitcnt lgkmcnt(1)
	v_or_b32_e32 v3, v3, v4
	s_waitcnt lgkmcnt(0)
	v_bitop3_b32 v0, v0, v2, v1 bitop3:0x80
	v_readlane_b32 s20, v3, 0
	v_readlane_b32 s21, v3, 1
	v_readlane_b32 s22, v3, 2
	v_readlane_b32 s23, v3, 3
	v_readlane_b32 s26, v0, 0
	v_readlane_b32 s27, v0, 1
	v_readlane_b32 s77, v0, 2
	v_readlane_b32 s78, v0, 3
	s_and_saveexec_b64 s[0:1], s[8:9]
	s_cbranch_execz .LBB0_1038
	v_mov_b32_e32 v0, s23
	v_mov_b32_e32 v1, s22
	v_cndmask_b32_e64 v0, v0, v1, s[14:15]
	v_mov_b32_e32 v1, s21
	v_cndmask_b32_e64 v0, v0, v1, s[12:13]
	v_mov_b32_e32 v1, s20
	v_cndmask_b32_e64 v0, v0, v1, s[10:11]
	v_and_b32_e32 v1, v0, v158
	v_cmp_ne_u32_e32 vcc, 0, v1
	s_and_b64 exec, exec, vcc
	s_cbranch_execz .LBB0_1038
	s_bcnt1_i32_b32 s24, s20
	v_mov_b32_e32 v1, s24
	s_bcnt1_i32_b32 s24, s21
	v_mov_b32_e32 v2, s24
	s_bcnt1_i32_b32 s24, s22
	v_cndmask_b32_e64 v1, v1, 0, s[10:11]
	v_cndmask_b32_e64 v2, 0, v2, s[16:17]
	v_mov_b32_e32 v3, s24
	v_and_b32_e32 v0, v0, v159
	v_cndmask_b32_e64 v3, 0, v3, s[18:19]
	v_bcnt_u32_b32 v0, v0, 0
	v_lshlrev_b32_e32 v1, 2, v1
	v_lshlrev_b32_e32 v2, 2, v2
	v_add3_u32 v1, s72, v1, v2
	v_lshlrev_b32_e32 v2, 2, v3
	v_lshlrev_b32_e32 v0, 2, v0
	v_add3_u32 v0, v1, v2, v0
	ds_write_b32 v0, v129

.LBB0_1040:
	s_mov_b32 s22, s32
	s_mov_b32 s23, s97
	s_add_i32 s29, s81, 0xffffff80
	s_and_b32 s29, s29, 0x80
	s_mulk_i32 s29, 0xa0
	v_add_u32_e32 v143, s29, v153
	ds_read_b128 v[88:91], v143
	ds_read_b128 v[92:95], v143 offset:64
	ds_read_b128 v[96:99], v143 offset:2560
	ds_read_b128 v[100:103], v143 offset:2624
	ds_read_b128 v[104:107], v143 offset:5120
	ds_read_b128 v[108:111], v143 offset:5184
	ds_read_b128 v[112:115], v143 offset:7680
	ds_read_b128 v[116:119], v143 offset:7744
	s_lshl_b64 s[20:21], 1, s22
	s_cmp_gt_u32 s22, 63
	s_cselect_b64 s[30:31], s[20:21], 0
	s_cselect_b64 s[20:21], 0, s[20:21]
	v_and_b32_e32 v0, s20, v234
	v_and_or_b32 v0, v235, s21, v0
	v_and_or_b32 v0, v238, s30, v0
	v_and_or_b32 v0, v239, s31, v0
	v_cmp_ne_u32_e32 vcc, 0, v0
	s_orn2_b64 s[20:21], vcc, exec
	s_lshl_b64 s[0:1], 1, s23
	s_cmp_gt_u32 s23, 63
	s_cselect_b64 s[30:31], s[0:1], 0
	s_cselect_b64 s[0:1], 0, s[0:1]
	v_and_b32_e32 v0, s0, v234
	v_and_or_b32 v0, v235, s1, v0
	v_and_or_b32 v0, v238, s30, v0
	v_and_or_b32 v0, v239, s31, v0
	v_cmp_ne_u32_e32 vcc, 0, v0
	s_orn2_b64 s[0:1], vcc, exec
.LBB0_1044:
	s_lshl_b32 s29, s22, 6
	v_subrev_u32_e32 v1, s29, v139
	s_lshl_b32 s29, s23, 6
	v_subrev_u32_e32 v0, s29, v139
	s_max_i32 s22, s22, s23
	s_cmp_ge_i32 s22, s76
	s_setprio 1
	v_cvt_f32_i32_e32 v147, v1
	v_cvt_f32_i32_e32 v141, v0
	s_mov_b64 s[22:23], -1
	s_cbranch_scc0 .LBB0_1046
	s_waitcnt lgkmcnt(7)
	v_mfma_f32_16x16x32_bf16 v[2:5], v[88:91], v[60:63], 0
	s_waitcnt lgkmcnt(5)
	v_mfma_f32_16x16x32_bf16 v[6:9], v[96:99], v[60:63], 0
	s_waitcnt lgkmcnt(3)
	v_mfma_f32_16x16x32_bf16 v[10:13], v[104:107], v[60:63], 0
	s_waitcnt lgkmcnt(1)
	v_mfma_f32_16x16x32_bf16 v[80:83], v[112:115], v[60:63], 0
	v_mfma_f32_16x16x32_bf16 v[2:5], v[92:95], v[56:59], v[2:5]
	v_mfma_f32_16x16x32_bf16 v[6:9], v[100:103], v[56:59], v[6:9]
	v_mfma_f32_16x16x32_bf16 v[10:13], v[108:111], v[56:59], v[10:13]
	s_waitcnt lgkmcnt(0)
	v_mfma_f32_16x16x32_bf16 v[80:83], v[116:119], v[56:59], v[80:83]
	s_setprio 0
	v_fma_f32 v14, -v146, v147, v192
	s_nop 1
	v_fmamk_f32 v2, v2, 0x3e38aa3b, v14
	v_cmp_gt_u32_e32 vcc, s70, v1
	v_add_f32_e32 v15, v146, v14
	s_and_b64 vcc, vcc, s[20:21]
	v_fmac_f32_e32 v15, 0x3e38aa3b, v3
	v_add_f32_e32 v3, v137, v14
	v_cndmask_b32_e32 v2, v179, v2, vcc
	v_cmp_lt_i32_e32 vcc, 0, v1
	v_fmac_f32_e32 v3, 0x3e38aa3b, v4
	v_add_f32_e32 v4, v188, v14
	s_and_b64 vcc, vcc, s[20:21]
	v_add_u32_e32 v14, -2, v1
	v_fmac_f32_e32 v4, 0x3e38aa3b, v5
	s_nop 0
	v_cndmask_b32_e32 v5, v179, v15, vcc
	v_cmp_gt_u32_e32 vcc, s70, v14
	s_and_b64 vcc, s[20:21], vcc
	v_add_u32_e32 v14, -3, v1
	v_cndmask_b32_e32 v3, v179, v3, vcc
	v_cmp_gt_u32_e32 vcc, s70, v14
	v_exp_f32_e32 v14, v2
	v_fma_f32 v2, -v146, v147, v189
	s_and_b64 vcc, s[20:21], vcc
	v_exp_f32_e32 v193, v3
	v_fmamk_f32 v3, v6, 0x3e38aa3b, v2
	v_add_u32_e32 v6, -16, v1
	v_cndmask_b32_e32 v4, v179, v4, vcc
	v_cmp_gt_u32_e32 vcc, s70, v6
	v_exp_f32_e32 v195, v4
	v_add_f32_e32 v4, v146, v2
	s_and_b64 vcc, s[20:21], vcc
	v_subrev_u32_e32 v6, 17, v1
	v_fmac_f32_e32 v4, 0x3e38aa3b, v7
	v_cndmask_b32_e32 v3, v179, v3, vcc
	v_cmp_gt_u32_e32 vcc, s70, v6
	v_exp_f32_e32 v15, v5
	v_add_f32_e32 v5, v137, v2
	s_and_b64 vcc, vcc, s[20:21]
	v_subrev_u32_e32 v6, 18, v1
	v_fmac_f32_e32 v5, 0x3e38aa3b, v8
	v_cndmask_b32_e32 v4, v179, v4, vcc
	v_cmp_gt_u32_e32 vcc, s70, v6
	v_add_f32_e32 v2, v188, v2
	s_and_b64 vcc, s[20:21], vcc
	v_subrev_u32_e32 v6, 19, v1
	v_fmac_f32_e32 v2, 0x3e38aa3b, v9
	v_cndmask_b32_e32 v5, v179, v5, vcc
	v_cmp_gt_u32_e32 vcc, s70, v6
	s_and_b64 vcc, s[20:21], vcc
	v_subrev_u32_e32 v6, 32, v1
	v_cndmask_b32_e32 v2, v179, v2, vcc
	v_exp_f32_e32 v199, v2
	v_fma_f32 v2, -v146, v147, v190
	v_exp_f32_e32 v196, v3
	v_fmamk_f32 v3, v10, 0x3e38aa3b, v2
	v_cmp_gt_u32_e32 vcc, s70, v6
	v_exp_f32_e32 v197, v4
	v_add_f32_e32 v4, v146, v2
	s_and_b64 vcc, s[20:21], vcc
	v_subrev_u32_e32 v6, 33, v1
	v_fmac_f32_e32 v4, 0x3e38aa3b, v11
	v_cndmask_b32_e32 v3, v179, v3, vcc
	v_cmp_gt_u32_e32 vcc, s70, v6
	v_exp_f32_e32 v198, v5
	v_add_f32_e32 v5, v137, v2
	s_and_b64 vcc, vcc, s[20:21]
	v_subrev_u32_e32 v6, 34, v1
	v_fmac_f32_e32 v5, 0x3e38aa3b, v12
	v_cndmask_b32_e32 v4, v179, v4, vcc
	v_cmp_gt_u32_e32 vcc, s70, v6
	v_add_f32_e32 v2, v188, v2
	s_and_b64 vcc, s[20:21], vcc
	v_subrev_u32_e32 v6, 35, v1
	v_fmac_f32_e32 v2, 0x3e38aa3b, v13
	v_cndmask_b32_e32 v5, v179, v5, vcc
	v_cmp_gt_u32_e32 vcc, s70, v6
	s_and_b64 vcc, s[20:21], vcc
	v_subrev_u32_e32 v6, 48, v1
	v_cndmask_b32_e32 v2, v179, v2, vcc
	v_exp_f32_e32 v221, v2
	v_fma_f32 v2, -v146, v147, v191
	v_exp_f32_e32 v218, v3
	v_fmamk_f32 v3, v80, 0x3e38aa3b, v2
	v_cmp_gt_u32_e32 vcc, s70, v6
	v_exp_f32_e32 v219, v4
	v_add_f32_e32 v4, v146, v2
	s_and_b64 vcc, s[20:21], vcc
	v_subrev_u32_e32 v6, 49, v1
	v_fmac_f32_e32 v4, 0x3e38aa3b, v81
	v_cndmask_b32_e32 v3, v179, v3, vcc
	v_cmp_gt_u32_e32 vcc, s70, v6
	v_exp_f32_e32 v220, v5
	v_add_f32_e32 v5, v137, v2
	s_and_b64 vcc, vcc, s[20:21]
	v_subrev_u32_e32 v6, 50, v1
	v_fmac_f32_e32 v5, 0x3e38aa3b, v82
	v_cndmask_b32_e32 v4, v179, v4, vcc
	v_cmp_gt_u32_e32 vcc, s70, v6
	v_add_f32_e32 v2, v188, v2
	s_and_b64 vcc, s[20:21], vcc
	v_subrev_u32_e32 v1, 51, v1
	v_fmac_f32_e32 v2, 0x3e38aa3b, v83
	v_cndmask_b32_e32 v5, v179, v5, vcc
	v_cmp_gt_u32_e32 vcc, s70, v1
	s_and_b64 vcc, s[20:21], vcc
	v_exp_f32_e32 v222, v3
	v_cndmask_b32_e32 v1, v179, v2, vcc
	v_exp_f32_e32 v223, v4
	v_exp_f32_e32 v224, v5
	ds_read_b128 v[2:5], v143 offset:40960
	ds_read_b128 v[6:9], v143 offset:43520
	ds_read_b128 v[10:13], v143 offset:46080
	ds_read_b128 v[80:83], v143 offset:48640
	v_exp_f32_e32 v1, v1
	s_nop 0
	v_cvt_pk_bf16_f32 v194, v14, v15
	v_cvt_pk_bf16_f32 v195, v193, v195
	v_cvt_pk_bf16_f32 v196, v196, v197
	v_cvt_pk_bf16_f32 v197, v198, v199
	s_setprio 1
	s_mov_b32 s30, s28
	s_mov_b32 s31, s28
	s_waitcnt lgkmcnt(0)
	v_mfma_f32_16x16x32_bf16 v[198:201], v[80:83], v[194:197], v[84:87]
	s_mov_b32 s29, s28
	v_mov_b64_e32 v[82:83], s[30:31]
	v_mov_b64_e32 v[80:81], s[28:29]
	v_mfma_f32_16x16x32_bf16 v[2:5], v[2:5], v[194:197], v[36:39]
	v_mfma_f32_16x16x32_bf16 v[6:9], v[6:9], v[194:197], v[40:43]
	v_mfma_f32_16x16x32_bf16 v[10:13], v[10:13], v[194:197], v[44:47]
	v_mfma_f32_16x16x32_bf16 v[194:197], v[80:83], v[194:197], v[32:35]
	s_setprio 0
	ds_read_b128 v[202:205], v143 offset:41024
	ds_read_b128 v[206:209], v143 offset:43584
	ds_read_b128 v[210:213], v143 offset:46144
	ds_read_b128 v[214:217], v143 offset:48704
	v_cvt_pk_bf16_f32 v218, v218, v219
	v_cvt_pk_bf16_f32 v219, v220, v221
	v_cvt_pk_bf16_f32 v220, v222, v223
	v_cvt_pk_bf16_f32 v221, v224, v1
	s_setprio 1
	s_waitcnt lgkmcnt(3)
	v_mfma_f32_16x16x32_bf16 v[2:5], v[202:205], v[218:221], v[2:5]
	s_waitcnt lgkmcnt(2)
	v_mfma_f32_16x16x32_bf16 v[6:9], v[206:209], v[218:221], v[6:9]
	s_waitcnt lgkmcnt(1)
	v_mfma_f32_16x16x32_bf16 v[10:13], v[210:213], v[218:221], v[10:13]
	s_waitcnt lgkmcnt(0)
	v_mfma_f32_16x16x32_bf16 v[198:201], v[214:217], v[218:221], v[198:201]
	v_mfma_f32_16x16x32_bf16 v[194:197], v[80:83], v[218:221], v[194:197]
	s_setprio 0
	s_sub_i32 s22, s81, 64
	s_and_b32 s22, s22, 0xc0
	s_mulk_i32 s22, 0xa0
	v_add_u32_e32 v193, s22, v153
	ds_read_b128 v[202:205], v193
	ds_read_b128 v[206:209], v193 offset:64
	ds_read_b128 v[210:213], v193 offset:2560
	ds_read_b128 v[214:217], v193 offset:2624
	ds_read_b128 v[218:221], v193 offset:5120
	ds_read_b128 v[222:225], v193 offset:5184
	ds_read_b128 v[226:229], v193 offset:7680
	ds_read_b128 v[230:233], v193 offset:7744
	s_setprio 1
	s_waitcnt lgkmcnt(7)
	v_mfma_f32_16x16x32_bf16 v[202:205], v[202:205], v[60:63], 0
	s_waitcnt lgkmcnt(6)
	v_mfma_f32_16x16x32_bf16 v[202:205], v[206:209], v[56:59], v[202:205]
	s_waitcnt lgkmcnt(5)
	v_mfma_f32_16x16x32_bf16 v[206:209], v[210:213], v[60:63], 0
	s_waitcnt lgkmcnt(4)
	v_mfma_f32_16x16x32_bf16 v[206:209], v[214:217], v[56:59], v[206:209]
	s_waitcnt lgkmcnt(3)
	v_mfma_f32_16x16x32_bf16 v[210:213], v[218:221], v[60:63], 0
	s_waitcnt lgkmcnt(1)
	v_mfma_f32_16x16x32_bf16 v[214:217], v[226:229], v[60:63], 0
	v_mfma_f32_16x16x32_bf16 v[210:213], v[222:225], v[56:59], v[210:213]
	s_waitcnt lgkmcnt(0)
	v_mfma_f32_16x16x32_bf16 v[214:217], v[230:233], v[56:59], v[214:217]
	s_setprio 0
	v_fma_f32 v1, -v146, v141, v192
	v_fmamk_f32 v14, v202, 0x3e38aa3b, v1
	v_cmp_gt_u32_e32 vcc, s70, v0
	v_add_f32_e32 v15, v146, v1
	s_and_b64 vcc, vcc, s[0:1]
	v_fmac_f32_e32 v15, 0x3e38aa3b, v203
	v_cndmask_b32_e32 v14, v179, v14, vcc
	v_cmp_lt_i32_e32 vcc, 0, v0
	v_add_f32_e32 v202, v137, v1
	s_and_b64 vcc, vcc, s[0:1]
	v_add_u32_e32 v203, -2, v0
	v_fmac_f32_e32 v202, 0x3e38aa3b, v204
	v_cndmask_b32_e32 v15, v179, v15, vcc
	v_cmp_gt_u32_e32 vcc, s70, v203
	s_and_b64 vcc, s[0:1], vcc
	v_add_f32_e32 v1, v188, v1
	v_cndmask_b32_e32 v202, v179, v202, vcc
	v_add_u32_e32 v203, -3, v0
	v_fmac_f32_e32 v1, 0x3e38aa3b, v205
	v_cmp_gt_u32_e32 vcc, s70, v203
	v_exp_f32_e32 v219, v202
	v_fma_f32 v202, -v146, v141, v189
	s_and_b64 vcc, s[0:1], vcc
	v_fmamk_f32 v203, v206, 0x3e38aa3b, v202
	v_add_u32_e32 v206, -16, v0
	v_cndmask_b32_e32 v1, v179, v1, vcc
	v_cmp_gt_u32_e32 vcc, s70, v206
	v_add_f32_e32 v204, v146, v202
	s_and_b64 vcc, s[0:1], vcc
	v_subrev_u32_e32 v206, 17, v0
	v_fmac_f32_e32 v204, 0x3e38aa3b, v207
	v_cndmask_b32_e32 v203, v179, v203, vcc
	v_cmp_gt_u32_e32 vcc, s70, v206
	v_add_f32_e32 v205, v137, v202
	s_and_b64 vcc, vcc, s[0:1]
	v_subrev_u32_e32 v206, 18, v0
	v_fmac_f32_e32 v205, 0x3e38aa3b, v208
	v_cndmask_b32_e32 v204, v179, v204, vcc
	v_cmp_gt_u32_e32 vcc, s70, v206
	v_add_f32_e32 v202, v188, v202
	s_and_b64 vcc, s[0:1], vcc
	v_subrev_u32_e32 v206, 19, v0
	v_fmac_f32_e32 v202, 0x3e38aa3b, v209
	v_cndmask_b32_e32 v205, v179, v205, vcc
	v_cmp_gt_u32_e32 vcc, s70, v206
	s_and_b64 vcc, s[0:1], vcc
	v_subrev_u32_e32 v206, 32, v0
	v_cndmask_b32_e32 v202, v179, v202, vcc
	v_exp_f32_e32 v223, v202
	v_fma_f32 v202, -v146, v141, v190
	v_exp_f32_e32 v220, v203
	v_fmamk_f32 v203, v210, 0x3e38aa3b, v202
	v_cmp_gt_u32_e32 vcc, s70, v206
	v_exp_f32_e32 v221, v204
	v_add_f32_e32 v204, v146, v202
	s_and_b64 vcc, s[0:1], vcc
	v_subrev_u32_e32 v206, 33, v0
	v_fmac_f32_e32 v204, 0x3e38aa3b, v211
	v_cndmask_b32_e32 v203, v179, v203, vcc
	v_cmp_gt_u32_e32 vcc, s70, v206
	v_exp_f32_e32 v222, v205
	v_add_f32_e32 v205, v137, v202
	s_and_b64 vcc, vcc, s[0:1]
	v_subrev_u32_e32 v206, 34, v0
	v_fmac_f32_e32 v205, 0x3e38aa3b, v212
	v_cndmask_b32_e32 v204, v179, v204, vcc
	v_cmp_gt_u32_e32 vcc, s70, v206
	v_add_f32_e32 v202, v188, v202
	s_and_b64 vcc, s[0:1], vcc
	v_subrev_u32_e32 v206, 35, v0
	v_fmac_f32_e32 v202, 0x3e38aa3b, v213
	v_cndmask_b32_e32 v205, v179, v205, vcc
	v_cmp_gt_u32_e32 vcc, s70, v206
	s_and_b64 vcc, s[0:1], vcc
	v_subrev_u32_e32 v206, 48, v0
	v_cndmask_b32_e32 v202, v179, v202, vcc
	v_exp_f32_e32 v227, v202
	v_fma_f32 v202, -v146, v141, v191
	v_exp_f32_e32 v224, v203
	v_fmamk_f32 v203, v214, 0x3e38aa3b, v202
	v_cmp_gt_u32_e32 vcc, s70, v206
	v_exp_f32_e32 v225, v204
	v_add_f32_e32 v204, v146, v202
	s_and_b64 vcc, s[0:1], vcc
	v_subrev_u32_e32 v206, 49, v0
	v_fmac_f32_e32 v204, 0x3e38aa3b, v215
	v_cndmask_b32_e32 v203, v179, v203, vcc
	v_cmp_gt_u32_e32 vcc, s70, v206
	v_exp_f32_e32 v226, v205
	v_add_f32_e32 v205, v137, v202
	s_and_b64 vcc, vcc, s[0:1]
	v_subrev_u32_e32 v206, 50, v0
	v_fmac_f32_e32 v205, 0x3e38aa3b, v216
	v_cndmask_b32_e32 v204, v179, v204, vcc
	v_cmp_gt_u32_e32 vcc, s70, v206
	v_add_f32_e32 v202, v188, v202
	s_and_b64 vcc, s[0:1], vcc
	v_subrev_u32_e32 v0, 51, v0
	v_fmac_f32_e32 v202, 0x3e38aa3b, v217
	v_cndmask_b32_e32 v205, v179, v205, vcc
	v_cmp_gt_u32_e32 vcc, s70, v0
	s_and_b64 vcc, s[0:1], vcc
	v_exp_f32_e32 v228, v203
	v_cndmask_b32_e32 v0, v179, v202, vcc
	v_exp_f32_e32 v229, v204
	v_exp_f32_e32 v230, v205
	ds_read_b128 v[202:205], v193 offset:40960
	ds_read_b128 v[206:209], v193 offset:43520
	ds_read_b128 v[210:213], v193 offset:46080
	ds_read_b128 v[214:217], v193 offset:48640
	v_exp_f32_e32 v14, v14
	v_exp_f32_e32 v15, v15
	v_exp_f32_e32 v1, v1
	v_exp_f32_e32 v231, v0
	s_nop 0
	v_cvt_pk_bf16_f32 v218, v14, v15
	v_cvt_pk_bf16_f32 v219, v219, v1
	v_cvt_pk_bf16_f32 v220, v220, v221
	v_cvt_pk_bf16_f32 v221, v222, v223
	s_setprio 1
	s_waitcnt lgkmcnt(3)
	v_mfma_f32_16x16x32_bf16 v[0:3], v[202:205], v[218:221], v[2:5]
	s_waitcnt lgkmcnt(2)
	v_mfma_f32_16x16x32_bf16 v[4:7], v[206:209], v[218:221], v[6:9]
	s_waitcnt lgkmcnt(1)
	v_mfma_f32_16x16x32_bf16 v[8:11], v[210:213], v[218:221], v[10:13]
	s_waitcnt lgkmcnt(0)
	v_mfma_f32_16x16x32_bf16 v[12:15], v[214:217], v[218:221], v[198:201]
	v_mfma_f32_16x16x32_bf16 v[194:197], v[80:83], v[218:221], v[194:197]
	s_setprio 0
	s_nop 0
	ds_read_b128 v[198:201], v193 offset:41024
	ds_read_b128 v[202:205], v193 offset:43584
	ds_read_b128 v[206:209], v193 offset:46144
	ds_read_b128 v[210:213], v193 offset:48704
	v_cvt_pk_bf16_f32 v214, v224, v225
	v_cvt_pk_bf16_f32 v215, v226, v227
	v_cvt_pk_bf16_f32 v216, v228, v229
	v_cvt_pk_bf16_f32 v217, v230, v231
	s_setprio 1
	s_waitcnt lgkmcnt(3)
	v_mfma_f32_16x16x32_bf16 v[0:3], v[198:201], v[214:217], v[0:3]
	s_mov_b64 s[22:23], 0
	s_waitcnt lgkmcnt(2)
	v_mfma_f32_16x16x32_bf16 v[4:7], v[202:205], v[214:217], v[4:7]
	s_waitcnt lgkmcnt(1)
	v_mfma_f32_16x16x32_bf16 v[8:11], v[206:209], v[214:217], v[8:11]
	s_waitcnt lgkmcnt(0)
	v_mfma_f32_16x16x32_bf16 v[12:15], v[210:213], v[214:217], v[12:15]
	v_mfma_f32_16x16x32_bf16 v[80:83], v[80:83], v[214:217], v[194:197]
